# in-loop prune keeps at most 280 entries per query (was 288)
# baseline (speedup 1.0000x reference)
.Lto_nost:
	v_mov_b32_e32 v0, s21
	s_waitcnt lgkmcnt(0)
	s_barrier
	ds_read_b32 v0, v0
	s_waitcnt lgkmcnt(0)
	v_cmp_ne_u32_e32 vcc, s9, v0
	s_and_b64 vcc, exec, vcc
	s_cbranch_vccnz .LBB0_1045
	s_nop 0
	v_readlane_b32 s0, v238, 0
	v_readlane_b32 s1, v238, 32
	s_sub_u32 s0, s0, s33
	s_sub_u32 s0, s0, 0x0
	s_lshr_b32 s78, s0, 2
	s_sub_u32 s1, s1, s33
	s_sub_u32 s1, s1, 0x1000
	s_lshr_b32 s16, s1, 2
	v_readlane_b32 s0, v239, 0
	v_readlane_b32 s1, v239, 32
	s_sub_u32 s0, s0, s33
	s_sub_u32 s0, s0, 0x800
	s_lshr_b32 s61, s0, 2
	s_sub_u32 s1, s1, s33
	s_sub_u32 s1, s1, 0x1800
	s_lshr_b32 s15, s1, 2
	v_readlane_b32 s0, v240, 0
	v_readlane_b32 s1, v240, 32
	s_sub_u32 s0, s0, s33
	s_sub_u32 s0, s0, 0x2000
	s_lshr_b32 s8, s0, 2
	s_sub_u32 s1, s1, s33
	s_sub_u32 s1, s1, 0x3000
	s_lshr_b32 s13, s1, 2
	v_readlane_b32 s0, v241, 0
	v_readlane_b32 s1, v241, 32
	s_sub_u32 s0, s0, s33
	s_sub_u32 s0, s0, 0x2800
	s_lshr_b32 s14, s0, 2
	s_sub_u32 s1, s1, s33
	s_sub_u32 s1, s1, 0x3800
	s_lshr_b32 s5, s1, 2
	v_and_b32_e32 v58, 15, v66
	v_lshlrev_b32_e32 v41, 4, v58
	v_sub_u32_e32 v40, v195, v41
	v_lshrrev_b32_e32 v57, 4, v66
	v_lshl_add_u32 v59, v57, 11, s33
	v_add_u32_e32 v60, v59, v41
	s_mov_b32 s22, 0
	s_mov_b32 s23, 0
	s_cmpk_gt_i32 s78, 0x118
	s_cselect_b32 s0, 0xffff, 0
	s_or_b32 s22, s22, s0
	s_cmpk_gt_i32 s61, 0x118
	s_cselect_b32 s0, 0xffff0000, 0
	s_or_b32 s22, s22, s0
	s_cmpk_gt_i32 s16, 0x118
	s_cselect_b32 s0, 0xffff, 0
	s_or_b32 s23, s23, s0
	s_cmpk_gt_i32 s15, 0x118
	s_cselect_b32 s0, 0xffff0000, 0
	s_or_b32 s23, s23, s0
	s_cmp_eq_u64 s[22:23], 0
	s_cbranch_scc1 .Lp2apr0_end
	v_mov_b32_e32 v32, s78
	v_mov_b32_e32 v41, s61
	v_mov_b32_e32 v42, s16
	v_mov_b32_e32 v43, s15
	s_nop 0
	v_mov_b32_dpp v32, v41 quad_perm:[0,1,2,3] row_mask:0x2 bank_mask:0xf
	v_mov_b32_dpp v32, v42 quad_perm:[0,1,2,3] row_mask:0x4 bank_mask:0xf
	v_mov_b32_dpp v32, v43 quad_perm:[0,1,2,3] row_mask:0x8 bank_mask:0xf
	v_mov_b32_e32 v33, s73
	v_mov_b32_e32 v41, s72
	v_mov_b32_e32 v42, s71
	v_mov_b32_e32 v43, s70
	s_nop 0
	v_mov_b32_dpp v33, v41 quad_perm:[0,1,2,3] row_mask:0x2 bank_mask:0xf
	v_mov_b32_dpp v33, v42 quad_perm:[0,1,2,3] row_mask:0x4 bank_mask:0xf
	v_mov_b32_dpp v33, v43 quad_perm:[0,1,2,3] row_mask:0x8 bank_mask:0xf
	ds_read_b128 v[0:3], v60
	ds_read_b128 v[4:7], v60 offset:256
	ds_read_b128 v[8:11], v60 offset:512
	ds_read_b128 v[12:15], v60 offset:768
	ds_read_b128 v[16:19], v60 offset:1024
	ds_read_b128 v[20:23], v60 offset:1280
	ds_read_b128 v[24:27], v60 offset:1536
	ds_read_b128 v[28:31], v60 offset:1792
	v_lshlrev_b32_e32 v41, 2, v58
	v_sub_u32_e32 v41, v32, v41
	s_waitcnt lgkmcnt(0)
	v_mov_b32_e32 v47, 16
	v_subrev_u32_e32 v42, 256, v41
	v_med3_i32 v43, v42, 0, 4
	v_add_u32_e32 v47, v47, v43
	v_cmp_lt_i32_e32 vcc, 0, v42
	v_cmp_lt_i32_e64 s[0:1], 1, v42
	v_cmp_lt_i32_e64 s[2:3], 2, v42
	v_cndmask_b32_e32 v16, 0, v16, vcc
	v_cmp_lt_i32_e32 vcc, 3, v42
	v_cndmask_b32_e64 v17, 0, v17, s[0:1]
	v_cndmask_b32_e64 v18, 0, v18, s[2:3]
	v_cndmask_b32_e32 v19, 0, v19, vcc
	v_subrev_u32_e32 v42, 320, v41
	v_med3_i32 v43, v42, 0, 4
	v_add_u32_e32 v47, v47, v43
	v_cmp_lt_i32_e32 vcc, 0, v42
	v_cmp_lt_i32_e64 s[0:1], 1, v42
	v_cmp_lt_i32_e64 s[2:3], 2, v42
	v_cndmask_b32_e32 v20, 0, v20, vcc
	v_cmp_lt_i32_e32 vcc, 3, v42
	v_cndmask_b32_e64 v21, 0, v21, s[0:1]
	v_cndmask_b32_e64 v22, 0, v22, s[2:3]
	v_cndmask_b32_e32 v23, 0, v23, vcc
	v_subrev_u32_e32 v42, 384, v41
	v_med3_i32 v43, v42, 0, 4
	v_add_u32_e32 v47, v47, v43
	v_cmp_lt_i32_e32 vcc, 0, v42
	v_cmp_lt_i32_e64 s[0:1], 1, v42
	v_cmp_lt_i32_e64 s[2:3], 2, v42
	v_cndmask_b32_e32 v24, 0, v24, vcc
	v_cmp_lt_i32_e32 vcc, 3, v42
	v_cndmask_b32_e64 v25, 0, v25, s[0:1]
	v_cndmask_b32_e64 v26, 0, v26, s[2:3]
	v_cndmask_b32_e32 v27, 0, v27, vcc
	v_subrev_u32_e32 v42, 448, v41
	v_med3_i32 v43, v42, 0, 4
	v_add_u32_e32 v47, v47, v43
	v_cmp_lt_i32_e32 vcc, 0, v42
	v_cmp_lt_i32_e64 s[0:1], 1, v42
	v_cmp_lt_i32_e64 s[2:3], 2, v42
	v_cndmask_b32_e32 v28, 0, v28, vcc
	v_cmp_lt_i32_e32 vcc, 3, v42
	v_cndmask_b32_e64 v29, 0, v29, s[0:1]
	v_cndmask_b32_e64 v30, 0, v30, s[2:3]
	v_cndmask_b32_e32 v31, 0, v31, vcc
	v_max3_u32 v35, v0, v1, v2
	v_max3_u32 v35, v3, v4, v35
	v_max3_u32 v35, v5, v6, v35
	v_max3_u32 v35, v7, v8, v35
	v_max3_u32 v35, v9, v10, v35
	v_max3_u32 v35, v11, v12, v35
	v_max3_u32 v35, v13, v14, v35
	v_max3_u32 v35, v15, v16, v35
	v_max3_u32 v35, v17, v18, v35
	v_max3_u32 v35, v19, v20, v35
	v_max3_u32 v35, v21, v22, v35
	v_max3_u32 v35, v23, v24, v35
	v_max3_u32 v35, v25, v26, v35
	v_max3_u32 v35, v27, v28, v35
	v_max3_u32 v35, v29, v30, v35
	v_max_u32_e32 v35, v31, v35
	s_nop 1
	v_max_u32_dpp v35, v35, v35 row_ror:1 row_mask:0xf bank_mask:0xf
	s_nop 1
	v_max_u32_dpp v35, v35, v35 row_ror:2 row_mask:0xf bank_mask:0xf
	s_nop 1
	v_max_u32_dpp v35, v35, v35 row_ror:4 row_mask:0xf bank_mask:0xf
	s_nop 1
	v_max_u32_dpp v35, v35, v35 row_ror:8 row_mask:0xf bank_mask:0xf
	v_and_b32_e32 v34, 0xffffe000, v33
	v_cmp_eq_u32_e32 vcc, 0, v33
	s_and_b64 vcc, vcc, s[22:23]
	s_cbranch_vccz .Lp2apr0_nomin
	v_add_u32_e32 v41, -1, v0
	v_add_u32_e32 v42, -1, v1
	v_min_u32_e32 v43, v41, v42
	v_add_u32_e32 v41, -1, v2
	v_add_u32_e32 v42, -1, v3
	v_min3_u32 v43, v41, v42, v43
	v_add_u32_e32 v41, -1, v4
	v_add_u32_e32 v42, -1, v5
	v_min3_u32 v43, v41, v42, v43
	v_add_u32_e32 v41, -1, v6
	v_add_u32_e32 v42, -1, v7
	v_min3_u32 v43, v41, v42, v43
	v_add_u32_e32 v41, -1, v8
	v_add_u32_e32 v42, -1, v9
	v_min3_u32 v43, v41, v42, v43
	v_add_u32_e32 v41, -1, v10
	v_add_u32_e32 v42, -1, v11
	v_min3_u32 v43, v41, v42, v43
	v_add_u32_e32 v41, -1, v12
	v_add_u32_e32 v42, -1, v13
	v_min3_u32 v43, v41, v42, v43
	v_add_u32_e32 v41, -1, v14
	v_add_u32_e32 v42, -1, v15
	v_min3_u32 v43, v41, v42, v43
	v_add_u32_e32 v41, -1, v16
	v_add_u32_e32 v42, -1, v17
	v_min3_u32 v43, v41, v42, v43
	v_add_u32_e32 v41, -1, v18
	v_add_u32_e32 v42, -1, v19
	v_min3_u32 v43, v41, v42, v43
	v_add_u32_e32 v41, -1, v20
	v_add_u32_e32 v42, -1, v21
	v_min3_u32 v43, v41, v42, v43
	v_add_u32_e32 v41, -1, v22
	v_add_u32_e32 v42, -1, v23
	v_min3_u32 v43, v41, v42, v43
	v_add_u32_e32 v41, -1, v24
	v_add_u32_e32 v42, -1, v25
	v_min3_u32 v43, v41, v42, v43
	v_add_u32_e32 v41, -1, v26
	v_add_u32_e32 v42, -1, v27
	v_min3_u32 v43, v41, v42, v43
	v_add_u32_e32 v41, -1, v28
	v_add_u32_e32 v42, -1, v29
	v_min3_u32 v43, v41, v42, v43
	v_add_u32_e32 v41, -1, v30
	v_add_u32_e32 v42, -1, v31
	v_min3_u32 v43, v41, v42, v43
	s_nop 1
	v_min_u32_dpp v43, v43, v43 row_ror:1 row_mask:0xf bank_mask:0xf
	s_nop 1
	v_min_u32_dpp v43, v43, v43 row_ror:2 row_mask:0xf bank_mask:0xf
	s_nop 1
	v_min_u32_dpp v43, v43, v43 row_ror:4 row_mask:0xf bank_mask:0xf
	s_nop 1
	v_min_u32_dpp v43, v43, v43 row_ror:8 row_mask:0xf bank_mask:0xf
	v_add_u32_e32 v43, 1, v43
	v_cmp_eq_u32_e32 vcc, 0, v33
	s_nop 1
	v_cndmask_b32_e32 v34, v34, v43, vcc

.Lp2apr0_iter:
	v_sub_u32_e32 v38, v35, v34
	v_or_b32_e32 v41, 1, v38
	v_ffbh_u32_e32 v41, v41
	v_sub_u32_e32 v41, 26, v41
	v_max_i32_e32 v39, 0, v41
	v_mov_b32_e32 v36, 0
	v_sub_u32_e64 v56, v0, v34 clamp
	v_lshrrev_b32_e32 v56, v39, v56
	v_min_u32_e32 v48, 0x7f, v56
	v_sub_u32_e64 v56, v1, v34 clamp
	v_lshrrev_b32_e32 v56, v39, v56
	v_min_u32_e32 v56, 0x7f, v56
	v_lshl_or_b32 v48, v56, 8, v48
	v_sub_u32_e64 v56, v2, v34 clamp
	v_lshrrev_b32_e32 v56, v39, v56
	v_min_u32_e32 v56, 0x7f, v56
	v_lshl_or_b32 v48, v56, 16, v48
	v_sub_u32_e64 v56, v3, v34 clamp
	v_lshrrev_b32_e32 v56, v39, v56
	v_min_u32_e32 v56, 0x7f, v56
	v_lshl_or_b32 v48, v56, 24, v48
	v_sub_u32_e64 v56, v4, v34 clamp
	v_lshrrev_b32_e32 v56, v39, v56
	v_min_u32_e32 v49, 0x7f, v56
	v_sub_u32_e64 v56, v5, v34 clamp
	v_lshrrev_b32_e32 v56, v39, v56
	v_min_u32_e32 v56, 0x7f, v56
	v_lshl_or_b32 v49, v56, 8, v49
	v_sub_u32_e64 v56, v6, v34 clamp
	v_lshrrev_b32_e32 v56, v39, v56
	v_min_u32_e32 v56, 0x7f, v56
	v_lshl_or_b32 v49, v56, 16, v49
	v_sub_u32_e64 v56, v7, v34 clamp
	v_lshrrev_b32_e32 v56, v39, v56
	v_min_u32_e32 v56, 0x7f, v56
	v_lshl_or_b32 v49, v56, 24, v49
	v_sub_u32_e64 v56, v8, v34 clamp
	v_lshrrev_b32_e32 v56, v39, v56
	v_min_u32_e32 v50, 0x7f, v56
	v_sub_u32_e64 v56, v9, v34 clamp
	v_lshrrev_b32_e32 v56, v39, v56
	v_min_u32_e32 v56, 0x7f, v56
	v_lshl_or_b32 v50, v56, 8, v50
	v_sub_u32_e64 v56, v10, v34 clamp
	v_lshrrev_b32_e32 v56, v39, v56
	v_min_u32_e32 v56, 0x7f, v56
	v_lshl_or_b32 v50, v56, 16, v50
	v_sub_u32_e64 v56, v11, v34 clamp
	v_lshrrev_b32_e32 v56, v39, v56
	v_min_u32_e32 v56, 0x7f, v56
	v_lshl_or_b32 v50, v56, 24, v50
	v_sub_u32_e64 v56, v12, v34 clamp
	v_lshrrev_b32_e32 v56, v39, v56
	v_min_u32_e32 v51, 0x7f, v56
	v_sub_u32_e64 v56, v13, v34 clamp
	v_lshrrev_b32_e32 v56, v39, v56
	v_min_u32_e32 v56, 0x7f, v56
	v_lshl_or_b32 v51, v56, 8, v51
	v_sub_u32_e64 v56, v14, v34 clamp
	v_lshrrev_b32_e32 v56, v39, v56
	v_min_u32_e32 v56, 0x7f, v56
	v_lshl_or_b32 v51, v56, 16, v51
	v_sub_u32_e64 v56, v15, v34 clamp
	v_lshrrev_b32_e32 v56, v39, v56
	v_min_u32_e32 v56, 0x7f, v56
	v_lshl_or_b32 v51, v56, 24, v51
	v_sub_u32_e64 v56, v16, v34 clamp
	v_lshrrev_b32_e32 v56, v39, v56
	v_min_u32_e32 v52, 0x7f, v56
	v_sub_u32_e64 v56, v17, v34 clamp
	v_lshrrev_b32_e32 v56, v39, v56
	v_min_u32_e32 v56, 0x7f, v56
	v_lshl_or_b32 v52, v56, 8, v52
	v_sub_u32_e64 v56, v18, v34 clamp
	v_lshrrev_b32_e32 v56, v39, v56
	v_min_u32_e32 v56, 0x7f, v56
	v_lshl_or_b32 v52, v56, 16, v52
	v_sub_u32_e64 v56, v19, v34 clamp
	v_lshrrev_b32_e32 v56, v39, v56
	v_min_u32_e32 v56, 0x7f, v56
	v_lshl_or_b32 v52, v56, 24, v52
	v_sub_u32_e64 v56, v20, v34 clamp
	v_lshrrev_b32_e32 v56, v39, v56
	v_min_u32_e32 v53, 0x7f, v56
	v_sub_u32_e64 v56, v21, v34 clamp
	v_lshrrev_b32_e32 v56, v39, v56
	v_min_u32_e32 v56, 0x7f, v56
	v_lshl_or_b32 v53, v56, 8, v53
	v_sub_u32_e64 v56, v22, v34 clamp
	v_lshrrev_b32_e32 v56, v39, v56
	v_min_u32_e32 v56, 0x7f, v56
	v_lshl_or_b32 v53, v56, 16, v53
	v_sub_u32_e64 v56, v23, v34 clamp
	v_lshrrev_b32_e32 v56, v39, v56
	v_min_u32_e32 v56, 0x7f, v56
	v_lshl_or_b32 v53, v56, 24, v53
	v_sub_u32_e64 v56, v24, v34 clamp
	v_lshrrev_b32_e32 v56, v39, v56
	v_min_u32_e32 v54, 0x7f, v56
	v_sub_u32_e64 v56, v25, v34 clamp
	v_lshrrev_b32_e32 v56, v39, v56
	v_min_u32_e32 v56, 0x7f, v56
	v_lshl_or_b32 v54, v56, 8, v54
	v_sub_u32_e64 v56, v26, v34 clamp
	v_lshrrev_b32_e32 v56, v39, v56
	v_min_u32_e32 v56, 0x7f, v56
	v_lshl_or_b32 v54, v56, 16, v54
	v_sub_u32_e64 v56, v27, v34 clamp
	v_lshrrev_b32_e32 v56, v39, v56
	v_min_u32_e32 v56, 0x7f, v56
	v_lshl_or_b32 v54, v56, 24, v54
	v_sub_u32_e64 v56, v28, v34 clamp
	v_lshrrev_b32_e32 v56, v39, v56
	v_min_u32_e32 v55, 0x7f, v56
	v_sub_u32_e64 v56, v29, v34 clamp
	v_lshrrev_b32_e32 v56, v39, v56
	v_min_u32_e32 v56, 0x7f, v56
	v_lshl_or_b32 v55, v56, 8, v55
	v_sub_u32_e64 v56, v30, v34 clamp
	v_lshrrev_b32_e32 v56, v39, v56
	v_min_u32_e32 v56, 0x7f, v56
	v_lshl_or_b32 v55, v56, 16, v55
	v_sub_u32_e64 v56, v31, v34 clamp
	v_lshrrev_b32_e32 v56, v39, v56
	v_min_u32_e32 v56, 0x7f, v56
	v_lshl_or_b32 v55, v56, 24, v55
	v_or_b32_e32 v42, 0x20202020, v36
	v_subrev_u32_e32 v43, 0x80808080, v42
	v_mov_b32_e32 v44, 0
	v_sub_u32_e32 v41, v48, v43
	v_and_b32_e32 v41, 0x80808080, v41
	v_bcnt_u32_b32 v44, v41, v44
	v_sub_u32_e32 v45, v49, v43
	v_and_b32_e32 v45, 0x80808080, v45
	v_bcnt_u32_b32 v44, v45, v44
	v_sub_u32_e32 v41, v50, v43
	v_and_b32_e32 v41, 0x80808080, v41
	v_bcnt_u32_b32 v44, v41, v44
	v_sub_u32_e32 v45, v51, v43
	v_and_b32_e32 v45, 0x80808080, v45
	v_bcnt_u32_b32 v44, v45, v44
	v_sub_u32_e32 v41, v52, v43
	v_and_b32_e32 v41, 0x80808080, v41
	v_bcnt_u32_b32 v44, v41, v44
	v_sub_u32_e32 v45, v53, v43
	v_and_b32_e32 v45, 0x80808080, v45
	v_bcnt_u32_b32 v44, v45, v44
	v_sub_u32_e32 v41, v54, v43
	v_and_b32_e32 v41, 0x80808080, v41
	v_bcnt_u32_b32 v44, v41, v44
	v_sub_u32_e32 v45, v55, v43
	v_and_b32_e32 v45, 0x80808080, v45
	v_bcnt_u32_b32 v44, v45, v44
	v_mov_b32_e32 v45, v44
	s_nop 1
	v_add_u32_dpp v45, v45, v45 row_ror:1 row_mask:0xf bank_mask:0xf
	s_nop 1
	v_add_u32_dpp v45, v45, v45 row_ror:2 row_mask:0xf bank_mask:0xf
	s_nop 1
	v_add_u32_dpp v45, v45, v45 row_ror:4 row_mask:0xf bank_mask:0xf
	s_nop 1
	v_add_u32_dpp v45, v45, v45 row_ror:8 row_mask:0xf bank_mask:0xf
	s_nop 0
	v_cmp_le_u32_e32 vcc, 0x100, v45
	s_nop 1
	v_cndmask_b32_e32 v36, v36, v42, vcc
	v_cndmask_b32_e32 v46, v46, v45, vcc
	v_cndmask_b32_e32 v47, v47, v44, vcc
	v_or_b32_e32 v42, 0x10101010, v36
	v_subrev_u32_e32 v43, 0x80808080, v42
	v_mov_b32_e32 v44, 0
	v_sub_u32_e32 v41, v48, v43
	v_and_b32_e32 v41, 0x80808080, v41
	v_bcnt_u32_b32 v44, v41, v44
	v_sub_u32_e32 v45, v49, v43
	v_and_b32_e32 v45, 0x80808080, v45
	v_bcnt_u32_b32 v44, v45, v44
	v_sub_u32_e32 v41, v50, v43
	v_and_b32_e32 v41, 0x80808080, v41
	v_bcnt_u32_b32 v44, v41, v44
	v_sub_u32_e32 v45, v51, v43
	v_and_b32_e32 v45, 0x80808080, v45
	v_bcnt_u32_b32 v44, v45, v44
	v_sub_u32_e32 v41, v52, v43
	v_and_b32_e32 v41, 0x80808080, v41
	v_bcnt_u32_b32 v44, v41, v44
	v_sub_u32_e32 v45, v53, v43
	v_and_b32_e32 v45, 0x80808080, v45
	v_bcnt_u32_b32 v44, v45, v44
	v_sub_u32_e32 v41, v54, v43
	v_and_b32_e32 v41, 0x80808080, v41
	v_bcnt_u32_b32 v44, v41, v44
	v_sub_u32_e32 v45, v55, v43
	v_and_b32_e32 v45, 0x80808080, v45
	v_bcnt_u32_b32 v44, v45, v44
	v_mov_b32_e32 v45, v44
	s_nop 1
	v_add_u32_dpp v45, v45, v45 row_ror:1 row_mask:0xf bank_mask:0xf
	s_nop 1
	v_add_u32_dpp v45, v45, v45 row_ror:2 row_mask:0xf bank_mask:0xf
	s_nop 1
	v_add_u32_dpp v45, v45, v45 row_ror:4 row_mask:0xf bank_mask:0xf
	s_nop 1
	v_add_u32_dpp v45, v45, v45 row_ror:8 row_mask:0xf bank_mask:0xf
	s_nop 0
	v_cmp_le_u32_e32 vcc, 0x100, v45
	s_nop 1
	v_cndmask_b32_e32 v36, v36, v42, vcc
	v_cndmask_b32_e32 v46, v46, v45, vcc
	v_cndmask_b32_e32 v47, v47, v44, vcc
	v_or_b32_e32 v42, 0x8080808, v36
	v_subrev_u32_e32 v43, 0x80808080, v42
	v_mov_b32_e32 v44, 0
	v_sub_u32_e32 v41, v48, v43
	v_and_b32_e32 v41, 0x80808080, v41
	v_bcnt_u32_b32 v44, v41, v44
	v_sub_u32_e32 v45, v49, v43
	v_and_b32_e32 v45, 0x80808080, v45
	v_bcnt_u32_b32 v44, v45, v44
	v_sub_u32_e32 v41, v50, v43
	v_and_b32_e32 v41, 0x80808080, v41
	v_bcnt_u32_b32 v44, v41, v44
	v_sub_u32_e32 v45, v51, v43
	v_and_b32_e32 v45, 0x80808080, v45
	v_bcnt_u32_b32 v44, v45, v44
	v_sub_u32_e32 v41, v52, v43
	v_and_b32_e32 v41, 0x80808080, v41
	v_bcnt_u32_b32 v44, v41, v44
	v_sub_u32_e32 v45, v53, v43
	v_and_b32_e32 v45, 0x80808080, v45
	v_bcnt_u32_b32 v44, v45, v44
	v_sub_u32_e32 v41, v54, v43
	v_and_b32_e32 v41, 0x80808080, v41
	v_bcnt_u32_b32 v44, v41, v44
	v_sub_u32_e32 v45, v55, v43
	v_and_b32_e32 v45, 0x80808080, v45
	v_bcnt_u32_b32 v44, v45, v44
	v_mov_b32_e32 v45, v44
	s_nop 1
	v_add_u32_dpp v45, v45, v45 row_ror:1 row_mask:0xf bank_mask:0xf
	s_nop 1
	v_add_u32_dpp v45, v45, v45 row_ror:2 row_mask:0xf bank_mask:0xf
	s_nop 1
	v_add_u32_dpp v45, v45, v45 row_ror:4 row_mask:0xf bank_mask:0xf
	s_nop 1
	v_add_u32_dpp v45, v45, v45 row_ror:8 row_mask:0xf bank_mask:0xf
	s_nop 0
	v_cmp_le_u32_e32 vcc, 0x100, v45
	s_nop 1
	v_cndmask_b32_e32 v36, v36, v42, vcc
	v_cndmask_b32_e32 v46, v46, v45, vcc
	v_cndmask_b32_e32 v47, v47, v44, vcc
	v_or_b32_e32 v42, 0x4040404, v36
	v_subrev_u32_e32 v43, 0x80808080, v42
	v_mov_b32_e32 v44, 0
	v_sub_u32_e32 v41, v48, v43
	v_and_b32_e32 v41, 0x80808080, v41
	v_bcnt_u32_b32 v44, v41, v44
	v_sub_u32_e32 v45, v49, v43
	v_and_b32_e32 v45, 0x80808080, v45
	v_bcnt_u32_b32 v44, v45, v44
	v_sub_u32_e32 v41, v50, v43
	v_and_b32_e32 v41, 0x80808080, v41
	v_bcnt_u32_b32 v44, v41, v44
	v_sub_u32_e32 v45, v51, v43
	v_and_b32_e32 v45, 0x80808080, v45
	v_bcnt_u32_b32 v44, v45, v44
	v_sub_u32_e32 v41, v52, v43
	v_and_b32_e32 v41, 0x80808080, v41
	v_bcnt_u32_b32 v44, v41, v44
	v_sub_u32_e32 v45, v53, v43
	v_and_b32_e32 v45, 0x80808080, v45
	v_bcnt_u32_b32 v44, v45, v44
	v_sub_u32_e32 v41, v54, v43
	v_and_b32_e32 v41, 0x80808080, v41
	v_bcnt_u32_b32 v44, v41, v44
	v_sub_u32_e32 v45, v55, v43
	v_and_b32_e32 v45, 0x80808080, v45
	v_bcnt_u32_b32 v44, v45, v44
	v_mov_b32_e32 v45, v44
	s_nop 1
	v_add_u32_dpp v45, v45, v45 row_ror:1 row_mask:0xf bank_mask:0xf
	s_nop 1
	v_add_u32_dpp v45, v45, v45 row_ror:2 row_mask:0xf bank_mask:0xf
	s_nop 1
	v_add_u32_dpp v45, v45, v45 row_ror:4 row_mask:0xf bank_mask:0xf
	s_nop 1
	v_add_u32_dpp v45, v45, v45 row_ror:8 row_mask:0xf bank_mask:0xf
	s_nop 0
	v_cmp_le_u32_e32 vcc, 0x100, v45
	s_nop 1
	v_cndmask_b32_e32 v36, v36, v42, vcc
	v_cndmask_b32_e32 v46, v46, v45, vcc
	v_cndmask_b32_e32 v47, v47, v44, vcc
	v_or_b32_e32 v42, 0x2020202, v36
	v_subrev_u32_e32 v43, 0x80808080, v42
	v_mov_b32_e32 v44, 0
	v_sub_u32_e32 v41, v48, v43
	v_and_b32_e32 v41, 0x80808080, v41
	v_bcnt_u32_b32 v44, v41, v44
	v_sub_u32_e32 v45, v49, v43
	v_and_b32_e32 v45, 0x80808080, v45
	v_bcnt_u32_b32 v44, v45, v44
	v_sub_u32_e32 v41, v50, v43
	v_and_b32_e32 v41, 0x80808080, v41
	v_bcnt_u32_b32 v44, v41, v44
	v_sub_u32_e32 v45, v51, v43
	v_and_b32_e32 v45, 0x80808080, v45
	v_bcnt_u32_b32 v44, v45, v44
	v_sub_u32_e32 v41, v52, v43
	v_and_b32_e32 v41, 0x80808080, v41
	v_bcnt_u32_b32 v44, v41, v44
	v_sub_u32_e32 v45, v53, v43
	v_and_b32_e32 v45, 0x80808080, v45
	v_bcnt_u32_b32 v44, v45, v44
	v_sub_u32_e32 v41, v54, v43
	v_and_b32_e32 v41, 0x80808080, v41
	v_bcnt_u32_b32 v44, v41, v44
	v_sub_u32_e32 v45, v55, v43
	v_and_b32_e32 v45, 0x80808080, v45
	v_bcnt_u32_b32 v44, v45, v44
	v_mov_b32_e32 v45, v44
	s_nop 1
	v_add_u32_dpp v45, v45, v45 row_ror:1 row_mask:0xf bank_mask:0xf
	s_nop 1
	v_add_u32_dpp v45, v45, v45 row_ror:2 row_mask:0xf bank_mask:0xf
	s_nop 1
	v_add_u32_dpp v45, v45, v45 row_ror:4 row_mask:0xf bank_mask:0xf
	s_nop 1
	v_add_u32_dpp v45, v45, v45 row_ror:8 row_mask:0xf bank_mask:0xf
	s_nop 0
	v_cmp_le_u32_e32 vcc, 0x100, v45
	s_nop 1
	v_cndmask_b32_e32 v36, v36, v42, vcc
	v_cndmask_b32_e32 v46, v46, v45, vcc
	v_cndmask_b32_e32 v47, v47, v44, vcc
	v_or_b32_e32 v42, 0x1010101, v36
	v_subrev_u32_e32 v43, 0x80808080, v42
	v_mov_b32_e32 v44, 0
	v_sub_u32_e32 v41, v48, v43
	v_and_b32_e32 v41, 0x80808080, v41
	v_bcnt_u32_b32 v44, v41, v44
	v_sub_u32_e32 v45, v49, v43
	v_and_b32_e32 v45, 0x80808080, v45
	v_bcnt_u32_b32 v44, v45, v44
	v_sub_u32_e32 v41, v50, v43
	v_and_b32_e32 v41, 0x80808080, v41
	v_bcnt_u32_b32 v44, v41, v44
	v_sub_u32_e32 v45, v51, v43
	v_and_b32_e32 v45, 0x80808080, v45
	v_bcnt_u32_b32 v44, v45, v44
	v_sub_u32_e32 v41, v52, v43
	v_and_b32_e32 v41, 0x80808080, v41
	v_bcnt_u32_b32 v44, v41, v44
	v_sub_u32_e32 v45, v53, v43
	v_and_b32_e32 v45, 0x80808080, v45
	v_bcnt_u32_b32 v44, v45, v44
	v_sub_u32_e32 v41, v54, v43
	v_and_b32_e32 v41, 0x80808080, v41
	v_bcnt_u32_b32 v44, v41, v44
	v_sub_u32_e32 v45, v55, v43
	v_and_b32_e32 v45, 0x80808080, v45
	v_bcnt_u32_b32 v44, v45, v44
	v_mov_b32_e32 v45, v44
	s_nop 1
	v_add_u32_dpp v45, v45, v45 row_ror:1 row_mask:0xf bank_mask:0xf
	s_nop 1
	v_add_u32_dpp v45, v45, v45 row_ror:2 row_mask:0xf bank_mask:0xf
	s_nop 1
	v_add_u32_dpp v45, v45, v45 row_ror:4 row_mask:0xf bank_mask:0xf
	s_nop 1
	v_add_u32_dpp v45, v45, v45 row_ror:8 row_mask:0xf bank_mask:0xf
	s_nop 0
	v_cmp_le_u32_e32 vcc, 0x100, v45
	s_nop 1
	v_cndmask_b32_e32 v36, v36, v42, vcc
	v_cndmask_b32_e32 v46, v46, v45, vcc
	v_cndmask_b32_e32 v47, v47, v44, vcc
	v_and_b32_e32 v41, 0x7f, v36
	v_lshlrev_b32_e32 v41, v39, v41
	v_add_u32_e32 v41, v34, v41
	v_cmp_ge_u32_e32 vcc, 0x118, v46
	v_cmp_eq_u32_e64 s[0:1], 0, v39
	v_lshlrev_b32_e32 v42, v39, v200
	v_add_u32_e32 v42, -1, v42
	s_or_b64 vcc, vcc, s[0:1]
	s_andn2_b64 s[0:1], vcc, s[50:51]
	s_nor_b64 s[2:3], vcc, s[50:51]
	s_or_b64 s[50:51], s[50:51], vcc
	v_add_u32_e64 v42, v41, v42 clamp
	v_min_u32_e32 v42, v42, v35
	v_cndmask_b32_e64 v37, v37, v41, s[0:1]
	v_cndmask_b32_e64 v62, v62, v47, s[0:1]
	v_cndmask_b32_e64 v35, v35, v42, s[2:3]
	v_cndmask_b32_e64 v34, v34, v41, s[2:3]
	s_cmp_eq_u64 s[50:51], -1
	s_cbranch_scc0 .Lp2apr0_iter
	s_mov_b64 exec, s[22:23]
	v_mov_b32_e32 v61, v62
	s_nop 1
	v_add_u32_dpp v61, v61, v61 row_shr:1 row_mask:0xf bank_mask:0xf bound_ctrl:1
	s_nop 1
	v_add_u32_dpp v61, v61, v61 row_shr:2 row_mask:0xf bank_mask:0xf bound_ctrl:1
	s_nop 1
	v_add_u32_dpp v61, v61, v61 row_shr:4 row_mask:0xf bank_mask:0xf bound_ctrl:1
	s_nop 1
	v_add_u32_dpp v61, v61, v61 row_shr:8 row_mask:0xf bank_mask:0xf bound_ctrl:1
	v_sub_u32_e32 v62, v61, v62
	v_lshl_add_u32 v41, v62, 2, v59
	v_add_u32_e32 v41, -4, v41
	v_cmpx_ge_u32_e32 vcc, v0, v37
	v_add_u32_e32 v41, 4, v41
	ds_write_b32 v41, v0
	s_mov_b64 exec, s[22:23]
	v_cmpx_ge_u32_e32 vcc, v1, v37
	v_add_u32_e32 v41, 4, v41
	ds_write_b32 v41, v1
	s_mov_b64 exec, s[22:23]
	v_cmpx_ge_u32_e32 vcc, v2, v37
	v_add_u32_e32 v41, 4, v41
	ds_write_b32 v41, v2
	s_mov_b64 exec, s[22:23]
	v_cmpx_ge_u32_e32 vcc, v3, v37
	v_add_u32_e32 v41, 4, v41
	ds_write_b32 v41, v3
	s_mov_b64 exec, s[22:23]
	v_cmpx_ge_u32_e32 vcc, v4, v37
	v_add_u32_e32 v41, 4, v41
	ds_write_b32 v41, v4
	s_mov_b64 exec, s[22:23]
	v_cmpx_ge_u32_e32 vcc, v5, v37
	v_add_u32_e32 v41, 4, v41
	ds_write_b32 v41, v5
	s_mov_b64 exec, s[22:23]
	v_cmpx_ge_u32_e32 vcc, v6, v37
	v_add_u32_e32 v41, 4, v41
	ds_write_b32 v41, v6
	s_mov_b64 exec, s[22:23]
	v_cmpx_ge_u32_e32 vcc, v7, v37
	v_add_u32_e32 v41, 4, v41
	ds_write_b32 v41, v7
	s_mov_b64 exec, s[22:23]
	v_cmpx_ge_u32_e32 vcc, v8, v37
	v_add_u32_e32 v41, 4, v41
	ds_write_b32 v41, v8
	s_mov_b64 exec, s[22:23]
	v_cmpx_ge_u32_e32 vcc, v9, v37
	v_add_u32_e32 v41, 4, v41
	ds_write_b32 v41, v9
	s_mov_b64 exec, s[22:23]
	v_cmpx_ge_u32_e32 vcc, v10, v37
	v_add_u32_e32 v41, 4, v41
	ds_write_b32 v41, v10
	s_mov_b64 exec, s[22:23]
	v_cmpx_ge_u32_e32 vcc, v11, v37
	v_add_u32_e32 v41, 4, v41
	ds_write_b32 v41, v11
	s_mov_b64 exec, s[22:23]
	v_cmpx_ge_u32_e32 vcc, v12, v37
	v_add_u32_e32 v41, 4, v41
	ds_write_b32 v41, v12
	s_mov_b64 exec, s[22:23]
	v_cmpx_ge_u32_e32 vcc, v13, v37
	v_add_u32_e32 v41, 4, v41
	ds_write_b32 v41, v13
	s_mov_b64 exec, s[22:23]
	v_cmpx_ge_u32_e32 vcc, v14, v37
	v_add_u32_e32 v41, 4, v41
	ds_write_b32 v41, v14
	s_mov_b64 exec, s[22:23]
	v_cmpx_ge_u32_e32 vcc, v15, v37
	v_add_u32_e32 v41, 4, v41
	ds_write_b32 v41, v15
	s_mov_b64 exec, s[22:23]
	v_cmpx_ge_u32_e32 vcc, v16, v37
	v_add_u32_e32 v41, 4, v41
	ds_write_b32 v41, v16
	s_mov_b64 exec, s[22:23]
	v_cmpx_ge_u32_e32 vcc, v17, v37
	v_add_u32_e32 v41, 4, v41
	ds_write_b32 v41, v17
	s_mov_b64 exec, s[22:23]
	v_cmpx_ge_u32_e32 vcc, v18, v37
	v_add_u32_e32 v41, 4, v41
	ds_write_b32 v41, v18
	s_mov_b64 exec, s[22:23]
	v_cmpx_ge_u32_e32 vcc, v19, v37
	v_add_u32_e32 v41, 4, v41
	ds_write_b32 v41, v19
	s_mov_b64 exec, s[22:23]
	v_cmpx_ge_u32_e32 vcc, v20, v37
	v_add_u32_e32 v41, 4, v41
	ds_write_b32 v41, v20
	s_mov_b64 exec, s[22:23]
	v_cmpx_ge_u32_e32 vcc, v21, v37
	v_add_u32_e32 v41, 4, v41
	ds_write_b32 v41, v21
	s_mov_b64 exec, s[22:23]
	v_cmpx_ge_u32_e32 vcc, v22, v37
	v_add_u32_e32 v41, 4, v41
	ds_write_b32 v41, v22
	s_mov_b64 exec, s[22:23]
	v_cmpx_ge_u32_e32 vcc, v23, v37
	v_add_u32_e32 v41, 4, v41
	ds_write_b32 v41, v23
	s_mov_b64 exec, s[22:23]
	v_cmpx_ge_u32_e32 vcc, v24, v37
	v_add_u32_e32 v41, 4, v41
	ds_write_b32 v41, v24
	s_mov_b64 exec, s[22:23]
	v_cmpx_ge_u32_e32 vcc, v25, v37
	v_add_u32_e32 v41, 4, v41
	ds_write_b32 v41, v25
	s_mov_b64 exec, s[22:23]
	v_cmpx_ge_u32_e32 vcc, v26, v37
	v_add_u32_e32 v41, 4, v41
	ds_write_b32 v41, v26
	s_mov_b64 exec, s[22:23]
	v_cmpx_ge_u32_e32 vcc, v27, v37
	v_add_u32_e32 v41, 4, v41
	ds_write_b32 v41, v27
	s_mov_b64 exec, s[22:23]
	v_cmpx_ge_u32_e32 vcc, v28, v37
	v_add_u32_e32 v41, 4, v41
	ds_write_b32 v41, v28
	s_mov_b64 exec, s[22:23]
	v_cmpx_ge_u32_e32 vcc, v29, v37
	v_add_u32_e32 v41, 4, v41
	ds_write_b32 v41, v29
	s_mov_b64 exec, s[22:23]
	v_cmpx_ge_u32_e32 vcc, v30, v37
	v_add_u32_e32 v41, 4, v41
	ds_write_b32 v41, v30
	s_mov_b64 exec, s[22:23]
	v_cmpx_ge_u32_e32 vcc, v31, v37
	v_add_u32_e32 v41, 4, v41
	ds_write_b32 v41, v31
	s_mov_b64 exec, s[22:23]
	s_mov_b64 exec, -1
	v_and_b32_e32 v41, 0xffffe000, v37
	v_ashrrev_i32_e32 v42, 31, v41
	v_not_b32_e32 v42, v42
	v_or_b32_e32 v42, 0x80000000, v42
	v_xor_b32_e32 v63, v41, v42
	s_cmpk_lt_i32 s78, 0x119
	s_cbranch_scc1 .Lp2apr0_o0
	v_readlane_b32 s0, v63, 0
	v_readlane_b32 s73, v37, 0
	v_readlane_b32 s78, v61, 15
	v_mov_b32_e32 v231, s0
.Lp2apr0_o0:
	s_cmpk_lt_i32 s61, 0x119
	s_cbranch_scc1 .Lp2apr0_o1
	v_readlane_b32 s0, v63, 16
	v_readlane_b32 s72, v37, 16
	v_readlane_b32 s61, v61, 31
	v_mov_b32_e32 v229, s0
.Lp2apr0_o1:
	s_cmpk_lt_i32 s16, 0x119
	s_cbranch_scc1 .Lp2apr0_o2
	v_readlane_b32 s0, v63, 32
	v_readlane_b32 s71, v37, 32
	v_readlane_b32 s16, v61, 47
	v_mov_b32_e32 v230, s0
.Lp2apr0_o2:
	s_cmpk_lt_i32 s15, 0x119
	s_cbranch_scc1 .Lp2apr0_o3
	v_readlane_b32 s0, v63, 48
	v_readlane_b32 s70, v37, 48
	v_readlane_b32 s15, v61, 63
	v_mov_b32_e32 v232, s0
.Lp2apr0_o3:
.Lp2apr0_end:
	v_add_u32_e32 v59, 0x2000, v59
	v_add_u32_e32 v60, 0x2000, v60
	s_mov_b32 s22, 0
	s_mov_b32 s23, 0
	s_cmpk_gt_i32 s8, 0x118
	s_cselect_b32 s0, 0xffff, 0
	s_or_b32 s22, s22, s0
	s_cmpk_gt_i32 s14, 0x118
	s_cselect_b32 s0, 0xffff0000, 0
	s_or_b32 s22, s22, s0
	s_cmpk_gt_i32 s13, 0x118
	s_cselect_b32 s0, 0xffff, 0
	s_or_b32 s23, s23, s0
	s_cmpk_gt_i32 s5, 0x118
	s_cselect_b32 s0, 0xffff0000, 0
	s_or_b32 s23, s23, s0
	s_cmp_eq_u64 s[22:23], 0
	s_cbranch_scc1 .Lp2apr1_end
	v_mov_b32_e32 v32, s8
	v_mov_b32_e32 v41, s14
	v_mov_b32_e32 v42, s13
	v_mov_b32_e32 v43, s5
	s_nop 0
	v_mov_b32_dpp v32, v41 quad_perm:[0,1,2,3] row_mask:0x2 bank_mask:0xf
	v_mov_b32_dpp v32, v42 quad_perm:[0,1,2,3] row_mask:0x4 bank_mask:0xf
	v_mov_b32_dpp v32, v43 quad_perm:[0,1,2,3] row_mask:0x8 bank_mask:0xf
	v_mov_b32_e32 v33, s74
	v_mov_b32_e32 v41, s75
	v_mov_b32_e32 v42, s76
	v_mov_b32_e32 v43, s77
	s_nop 0
	v_mov_b32_dpp v33, v41 quad_perm:[0,1,2,3] row_mask:0x2 bank_mask:0xf
	v_mov_b32_dpp v33, v42 quad_perm:[0,1,2,3] row_mask:0x4 bank_mask:0xf
	v_mov_b32_dpp v33, v43 quad_perm:[0,1,2,3] row_mask:0x8 bank_mask:0xf
	ds_read_b128 v[0:3], v60
	ds_read_b128 v[4:7], v60 offset:256
	ds_read_b128 v[8:11], v60 offset:512
	ds_read_b128 v[12:15], v60 offset:768
	ds_read_b128 v[16:19], v60 offset:1024
	ds_read_b128 v[20:23], v60 offset:1280
	ds_read_b128 v[24:27], v60 offset:1536
	ds_read_b128 v[28:31], v60 offset:1792
	v_lshlrev_b32_e32 v41, 2, v58
	v_sub_u32_e32 v41, v32, v41
	s_waitcnt lgkmcnt(0)
	v_mov_b32_e32 v47, 16
	v_subrev_u32_e32 v42, 256, v41
	v_med3_i32 v43, v42, 0, 4
	v_add_u32_e32 v47, v47, v43
	v_cmp_lt_i32_e32 vcc, 0, v42
	v_cmp_lt_i32_e64 s[0:1], 1, v42
	v_cmp_lt_i32_e64 s[2:3], 2, v42
	v_cndmask_b32_e32 v16, 0, v16, vcc
	v_cmp_lt_i32_e32 vcc, 3, v42
	v_cndmask_b32_e64 v17, 0, v17, s[0:1]
	v_cndmask_b32_e64 v18, 0, v18, s[2:3]
	v_cndmask_b32_e32 v19, 0, v19, vcc
	v_subrev_u32_e32 v42, 320, v41
	v_med3_i32 v43, v42, 0, 4
	v_add_u32_e32 v47, v47, v43
	v_cmp_lt_i32_e32 vcc, 0, v42
	v_cmp_lt_i32_e64 s[0:1], 1, v42
	v_cmp_lt_i32_e64 s[2:3], 2, v42
	v_cndmask_b32_e32 v20, 0, v20, vcc
	v_cmp_lt_i32_e32 vcc, 3, v42
	v_cndmask_b32_e64 v21, 0, v21, s[0:1]
	v_cndmask_b32_e64 v22, 0, v22, s[2:3]
	v_cndmask_b32_e32 v23, 0, v23, vcc
	v_subrev_u32_e32 v42, 384, v41
	v_med3_i32 v43, v42, 0, 4
	v_add_u32_e32 v47, v47, v43
	v_cmp_lt_i32_e32 vcc, 0, v42
	v_cmp_lt_i32_e64 s[0:1], 1, v42
	v_cmp_lt_i32_e64 s[2:3], 2, v42
	v_cndmask_b32_e32 v24, 0, v24, vcc
	v_cmp_lt_i32_e32 vcc, 3, v42
	v_cndmask_b32_e64 v25, 0, v25, s[0:1]
	v_cndmask_b32_e64 v26, 0, v26, s[2:3]
	v_cndmask_b32_e32 v27, 0, v27, vcc
	v_subrev_u32_e32 v42, 448, v41
	v_med3_i32 v43, v42, 0, 4
	v_add_u32_e32 v47, v47, v43
	v_cmp_lt_i32_e32 vcc, 0, v42
	v_cmp_lt_i32_e64 s[0:1], 1, v42
	v_cmp_lt_i32_e64 s[2:3], 2, v42
	v_cndmask_b32_e32 v28, 0, v28, vcc
	v_cmp_lt_i32_e32 vcc, 3, v42
	v_cndmask_b32_e64 v29, 0, v29, s[0:1]
	v_cndmask_b32_e64 v30, 0, v30, s[2:3]
	v_cndmask_b32_e32 v31, 0, v31, vcc
	v_max3_u32 v35, v0, v1, v2
	v_max3_u32 v35, v3, v4, v35
	v_max3_u32 v35, v5, v6, v35
	v_max3_u32 v35, v7, v8, v35
	v_max3_u32 v35, v9, v10, v35
	v_max3_u32 v35, v11, v12, v35
	v_max3_u32 v35, v13, v14, v35
	v_max3_u32 v35, v15, v16, v35
	v_max3_u32 v35, v17, v18, v35
	v_max3_u32 v35, v19, v20, v35
	v_max3_u32 v35, v21, v22, v35
	v_max3_u32 v35, v23, v24, v35
	v_max3_u32 v35, v25, v26, v35
	v_max3_u32 v35, v27, v28, v35
	v_max3_u32 v35, v29, v30, v35
	v_max_u32_e32 v35, v31, v35
	s_nop 1
	v_max_u32_dpp v35, v35, v35 row_ror:1 row_mask:0xf bank_mask:0xf
	s_nop 1
	v_max_u32_dpp v35, v35, v35 row_ror:2 row_mask:0xf bank_mask:0xf
	s_nop 1
	v_max_u32_dpp v35, v35, v35 row_ror:4 row_mask:0xf bank_mask:0xf
	s_nop 1
	v_max_u32_dpp v35, v35, v35 row_ror:8 row_mask:0xf bank_mask:0xf
	v_and_b32_e32 v34, 0xffffe000, v33
	v_cmp_eq_u32_e32 vcc, 0, v33
	s_and_b64 vcc, vcc, s[22:23]
	s_cbranch_vccz .Lp2apr1_nomin
	v_add_u32_e32 v41, -1, v0
	v_add_u32_e32 v42, -1, v1
	v_min_u32_e32 v43, v41, v42
	v_add_u32_e32 v41, -1, v2
	v_add_u32_e32 v42, -1, v3
	v_min3_u32 v43, v41, v42, v43
	v_add_u32_e32 v41, -1, v4
	v_add_u32_e32 v42, -1, v5
	v_min3_u32 v43, v41, v42, v43
	v_add_u32_e32 v41, -1, v6
	v_add_u32_e32 v42, -1, v7
	v_min3_u32 v43, v41, v42, v43
	v_add_u32_e32 v41, -1, v8
	v_add_u32_e32 v42, -1, v9
	v_min3_u32 v43, v41, v42, v43
	v_add_u32_e32 v41, -1, v10
	v_add_u32_e32 v42, -1, v11
	v_min3_u32 v43, v41, v42, v43
	v_add_u32_e32 v41, -1, v12
	v_add_u32_e32 v42, -1, v13
	v_min3_u32 v43, v41, v42, v43
	v_add_u32_e32 v41, -1, v14
	v_add_u32_e32 v42, -1, v15
	v_min3_u32 v43, v41, v42, v43
	v_add_u32_e32 v41, -1, v16
	v_add_u32_e32 v42, -1, v17
	v_min3_u32 v43, v41, v42, v43
	v_add_u32_e32 v41, -1, v18
	v_add_u32_e32 v42, -1, v19
	v_min3_u32 v43, v41, v42, v43
	v_add_u32_e32 v41, -1, v20
	v_add_u32_e32 v42, -1, v21
	v_min3_u32 v43, v41, v42, v43
	v_add_u32_e32 v41, -1, v22
	v_add_u32_e32 v42, -1, v23
	v_min3_u32 v43, v41, v42, v43
	v_add_u32_e32 v41, -1, v24
	v_add_u32_e32 v42, -1, v25
	v_min3_u32 v43, v41, v42, v43
	v_add_u32_e32 v41, -1, v26
	v_add_u32_e32 v42, -1, v27
	v_min3_u32 v43, v41, v42, v43
	v_add_u32_e32 v41, -1, v28
	v_add_u32_e32 v42, -1, v29
	v_min3_u32 v43, v41, v42, v43
	v_add_u32_e32 v41, -1, v30
	v_add_u32_e32 v42, -1, v31
	v_min3_u32 v43, v41, v42, v43
	s_nop 1
	v_min_u32_dpp v43, v43, v43 row_ror:1 row_mask:0xf bank_mask:0xf
	s_nop 1
	v_min_u32_dpp v43, v43, v43 row_ror:2 row_mask:0xf bank_mask:0xf
	s_nop 1
	v_min_u32_dpp v43, v43, v43 row_ror:4 row_mask:0xf bank_mask:0xf
	s_nop 1
	v_min_u32_dpp v43, v43, v43 row_ror:8 row_mask:0xf bank_mask:0xf
	v_add_u32_e32 v43, 1, v43
	v_cmp_eq_u32_e32 vcc, 0, v33
	s_nop 1
	v_cndmask_b32_e32 v34, v34, v43, vcc

.Lp2apr1_iter:
	v_sub_u32_e32 v38, v35, v34
	v_or_b32_e32 v41, 1, v38
	v_ffbh_u32_e32 v41, v41
	v_sub_u32_e32 v41, 26, v41
	v_max_i32_e32 v39, 0, v41
	v_mov_b32_e32 v36, 0
	v_sub_u32_e64 v56, v0, v34 clamp
	v_lshrrev_b32_e32 v56, v39, v56
	v_min_u32_e32 v48, 0x7f, v56
	v_sub_u32_e64 v56, v1, v34 clamp
	v_lshrrev_b32_e32 v56, v39, v56
	v_min_u32_e32 v56, 0x7f, v56
	v_lshl_or_b32 v48, v56, 8, v48
	v_sub_u32_e64 v56, v2, v34 clamp
	v_lshrrev_b32_e32 v56, v39, v56
	v_min_u32_e32 v56, 0x7f, v56
	v_lshl_or_b32 v48, v56, 16, v48
	v_sub_u32_e64 v56, v3, v34 clamp
	v_lshrrev_b32_e32 v56, v39, v56
	v_min_u32_e32 v56, 0x7f, v56
	v_lshl_or_b32 v48, v56, 24, v48
	v_sub_u32_e64 v56, v4, v34 clamp
	v_lshrrev_b32_e32 v56, v39, v56
	v_min_u32_e32 v49, 0x7f, v56
	v_sub_u32_e64 v56, v5, v34 clamp
	v_lshrrev_b32_e32 v56, v39, v56
	v_min_u32_e32 v56, 0x7f, v56
	v_lshl_or_b32 v49, v56, 8, v49
	v_sub_u32_e64 v56, v6, v34 clamp
	v_lshrrev_b32_e32 v56, v39, v56
	v_min_u32_e32 v56, 0x7f, v56
	v_lshl_or_b32 v49, v56, 16, v49
	v_sub_u32_e64 v56, v7, v34 clamp
	v_lshrrev_b32_e32 v56, v39, v56
	v_min_u32_e32 v56, 0x7f, v56
	v_lshl_or_b32 v49, v56, 24, v49
	v_sub_u32_e64 v56, v8, v34 clamp
	v_lshrrev_b32_e32 v56, v39, v56
	v_min_u32_e32 v50, 0x7f, v56
	v_sub_u32_e64 v56, v9, v34 clamp
	v_lshrrev_b32_e32 v56, v39, v56
	v_min_u32_e32 v56, 0x7f, v56
	v_lshl_or_b32 v50, v56, 8, v50
	v_sub_u32_e64 v56, v10, v34 clamp
	v_lshrrev_b32_e32 v56, v39, v56
	v_min_u32_e32 v56, 0x7f, v56
	v_lshl_or_b32 v50, v56, 16, v50
	v_sub_u32_e64 v56, v11, v34 clamp
	v_lshrrev_b32_e32 v56, v39, v56
	v_min_u32_e32 v56, 0x7f, v56
	v_lshl_or_b32 v50, v56, 24, v50
	v_sub_u32_e64 v56, v12, v34 clamp
	v_lshrrev_b32_e32 v56, v39, v56
	v_min_u32_e32 v51, 0x7f, v56
	v_sub_u32_e64 v56, v13, v34 clamp
	v_lshrrev_b32_e32 v56, v39, v56
	v_min_u32_e32 v56, 0x7f, v56
	v_lshl_or_b32 v51, v56, 8, v51
	v_sub_u32_e64 v56, v14, v34 clamp
	v_lshrrev_b32_e32 v56, v39, v56
	v_min_u32_e32 v56, 0x7f, v56
	v_lshl_or_b32 v51, v56, 16, v51
	v_sub_u32_e64 v56, v15, v34 clamp
	v_lshrrev_b32_e32 v56, v39, v56
	v_min_u32_e32 v56, 0x7f, v56
	v_lshl_or_b32 v51, v56, 24, v51
	v_sub_u32_e64 v56, v16, v34 clamp
	v_lshrrev_b32_e32 v56, v39, v56
	v_min_u32_e32 v52, 0x7f, v56
	v_sub_u32_e64 v56, v17, v34 clamp
	v_lshrrev_b32_e32 v56, v39, v56
	v_min_u32_e32 v56, 0x7f, v56
	v_lshl_or_b32 v52, v56, 8, v52
	v_sub_u32_e64 v56, v18, v34 clamp
	v_lshrrev_b32_e32 v56, v39, v56
	v_min_u32_e32 v56, 0x7f, v56
	v_lshl_or_b32 v52, v56, 16, v52
	v_sub_u32_e64 v56, v19, v34 clamp
	v_lshrrev_b32_e32 v56, v39, v56
	v_min_u32_e32 v56, 0x7f, v56
	v_lshl_or_b32 v52, v56, 24, v52
	v_sub_u32_e64 v56, v20, v34 clamp
	v_lshrrev_b32_e32 v56, v39, v56
	v_min_u32_e32 v53, 0x7f, v56
	v_sub_u32_e64 v56, v21, v34 clamp
	v_lshrrev_b32_e32 v56, v39, v56
	v_min_u32_e32 v56, 0x7f, v56
	v_lshl_or_b32 v53, v56, 8, v53
	v_sub_u32_e64 v56, v22, v34 clamp
	v_lshrrev_b32_e32 v56, v39, v56
	v_min_u32_e32 v56, 0x7f, v56
	v_lshl_or_b32 v53, v56, 16, v53
	v_sub_u32_e64 v56, v23, v34 clamp
	v_lshrrev_b32_e32 v56, v39, v56
	v_min_u32_e32 v56, 0x7f, v56
	v_lshl_or_b32 v53, v56, 24, v53
	v_sub_u32_e64 v56, v24, v34 clamp
	v_lshrrev_b32_e32 v56, v39, v56
	v_min_u32_e32 v54, 0x7f, v56
	v_sub_u32_e64 v56, v25, v34 clamp
	v_lshrrev_b32_e32 v56, v39, v56
	v_min_u32_e32 v56, 0x7f, v56
	v_lshl_or_b32 v54, v56, 8, v54
	v_sub_u32_e64 v56, v26, v34 clamp
	v_lshrrev_b32_e32 v56, v39, v56
	v_min_u32_e32 v56, 0x7f, v56
	v_lshl_or_b32 v54, v56, 16, v54
	v_sub_u32_e64 v56, v27, v34 clamp
	v_lshrrev_b32_e32 v56, v39, v56
	v_min_u32_e32 v56, 0x7f, v56
	v_lshl_or_b32 v54, v56, 24, v54
	v_sub_u32_e64 v56, v28, v34 clamp
	v_lshrrev_b32_e32 v56, v39, v56
	v_min_u32_e32 v55, 0x7f, v56
	v_sub_u32_e64 v56, v29, v34 clamp
	v_lshrrev_b32_e32 v56, v39, v56
	v_min_u32_e32 v56, 0x7f, v56
	v_lshl_or_b32 v55, v56, 8, v55
	v_sub_u32_e64 v56, v30, v34 clamp
	v_lshrrev_b32_e32 v56, v39, v56
	v_min_u32_e32 v56, 0x7f, v56
	v_lshl_or_b32 v55, v56, 16, v55
	v_sub_u32_e64 v56, v31, v34 clamp
	v_lshrrev_b32_e32 v56, v39, v56
	v_min_u32_e32 v56, 0x7f, v56
	v_lshl_or_b32 v55, v56, 24, v55
	v_or_b32_e32 v42, 0x20202020, v36
	v_subrev_u32_e32 v43, 0x80808080, v42
	v_mov_b32_e32 v44, 0
	v_sub_u32_e32 v41, v48, v43
	v_and_b32_e32 v41, 0x80808080, v41
	v_bcnt_u32_b32 v44, v41, v44
	v_sub_u32_e32 v45, v49, v43
	v_and_b32_e32 v45, 0x80808080, v45
	v_bcnt_u32_b32 v44, v45, v44
	v_sub_u32_e32 v41, v50, v43
	v_and_b32_e32 v41, 0x80808080, v41
	v_bcnt_u32_b32 v44, v41, v44
	v_sub_u32_e32 v45, v51, v43
	v_and_b32_e32 v45, 0x80808080, v45
	v_bcnt_u32_b32 v44, v45, v44
	v_sub_u32_e32 v41, v52, v43
	v_and_b32_e32 v41, 0x80808080, v41
	v_bcnt_u32_b32 v44, v41, v44
	v_sub_u32_e32 v45, v53, v43
	v_and_b32_e32 v45, 0x80808080, v45
	v_bcnt_u32_b32 v44, v45, v44
	v_sub_u32_e32 v41, v54, v43
	v_and_b32_e32 v41, 0x80808080, v41
	v_bcnt_u32_b32 v44, v41, v44
	v_sub_u32_e32 v45, v55, v43
	v_and_b32_e32 v45, 0x80808080, v45
	v_bcnt_u32_b32 v44, v45, v44
	v_mov_b32_e32 v45, v44
	s_nop 1
	v_add_u32_dpp v45, v45, v45 row_ror:1 row_mask:0xf bank_mask:0xf
	s_nop 1
	v_add_u32_dpp v45, v45, v45 row_ror:2 row_mask:0xf bank_mask:0xf
	s_nop 1
	v_add_u32_dpp v45, v45, v45 row_ror:4 row_mask:0xf bank_mask:0xf
	s_nop 1
	v_add_u32_dpp v45, v45, v45 row_ror:8 row_mask:0xf bank_mask:0xf
	s_nop 0
	v_cmp_le_u32_e32 vcc, 0x100, v45
	s_nop 1
	v_cndmask_b32_e32 v36, v36, v42, vcc
	v_cndmask_b32_e32 v46, v46, v45, vcc
	v_cndmask_b32_e32 v47, v47, v44, vcc
	v_or_b32_e32 v42, 0x10101010, v36
	v_subrev_u32_e32 v43, 0x80808080, v42
	v_mov_b32_e32 v44, 0
	v_sub_u32_e32 v41, v48, v43
	v_and_b32_e32 v41, 0x80808080, v41
	v_bcnt_u32_b32 v44, v41, v44
	v_sub_u32_e32 v45, v49, v43
	v_and_b32_e32 v45, 0x80808080, v45
	v_bcnt_u32_b32 v44, v45, v44
	v_sub_u32_e32 v41, v50, v43
	v_and_b32_e32 v41, 0x80808080, v41
	v_bcnt_u32_b32 v44, v41, v44
	v_sub_u32_e32 v45, v51, v43
	v_and_b32_e32 v45, 0x80808080, v45
	v_bcnt_u32_b32 v44, v45, v44
	v_sub_u32_e32 v41, v52, v43
	v_and_b32_e32 v41, 0x80808080, v41
	v_bcnt_u32_b32 v44, v41, v44
	v_sub_u32_e32 v45, v53, v43
	v_and_b32_e32 v45, 0x80808080, v45
	v_bcnt_u32_b32 v44, v45, v44
	v_sub_u32_e32 v41, v54, v43
	v_and_b32_e32 v41, 0x80808080, v41
	v_bcnt_u32_b32 v44, v41, v44
	v_sub_u32_e32 v45, v55, v43
	v_and_b32_e32 v45, 0x80808080, v45
	v_bcnt_u32_b32 v44, v45, v44
	v_mov_b32_e32 v45, v44
	s_nop 1
	v_add_u32_dpp v45, v45, v45 row_ror:1 row_mask:0xf bank_mask:0xf
	s_nop 1
	v_add_u32_dpp v45, v45, v45 row_ror:2 row_mask:0xf bank_mask:0xf
	s_nop 1
	v_add_u32_dpp v45, v45, v45 row_ror:4 row_mask:0xf bank_mask:0xf
	s_nop 1
	v_add_u32_dpp v45, v45, v45 row_ror:8 row_mask:0xf bank_mask:0xf
	s_nop 0
	v_cmp_le_u32_e32 vcc, 0x100, v45
	s_nop 1
	v_cndmask_b32_e32 v36, v36, v42, vcc
	v_cndmask_b32_e32 v46, v46, v45, vcc
	v_cndmask_b32_e32 v47, v47, v44, vcc
	v_or_b32_e32 v42, 0x8080808, v36
	v_subrev_u32_e32 v43, 0x80808080, v42
	v_mov_b32_e32 v44, 0
	v_sub_u32_e32 v41, v48, v43
	v_and_b32_e32 v41, 0x80808080, v41
	v_bcnt_u32_b32 v44, v41, v44
	v_sub_u32_e32 v45, v49, v43
	v_and_b32_e32 v45, 0x80808080, v45
	v_bcnt_u32_b32 v44, v45, v44
	v_sub_u32_e32 v41, v50, v43
	v_and_b32_e32 v41, 0x80808080, v41
	v_bcnt_u32_b32 v44, v41, v44
	v_sub_u32_e32 v45, v51, v43
	v_and_b32_e32 v45, 0x80808080, v45
	v_bcnt_u32_b32 v44, v45, v44
	v_sub_u32_e32 v41, v52, v43
	v_and_b32_e32 v41, 0x80808080, v41
	v_bcnt_u32_b32 v44, v41, v44
	v_sub_u32_e32 v45, v53, v43
	v_and_b32_e32 v45, 0x80808080, v45
	v_bcnt_u32_b32 v44, v45, v44
	v_sub_u32_e32 v41, v54, v43
	v_and_b32_e32 v41, 0x80808080, v41
	v_bcnt_u32_b32 v44, v41, v44
	v_sub_u32_e32 v45, v55, v43
	v_and_b32_e32 v45, 0x80808080, v45
	v_bcnt_u32_b32 v44, v45, v44
	v_mov_b32_e32 v45, v44
	s_nop 1
	v_add_u32_dpp v45, v45, v45 row_ror:1 row_mask:0xf bank_mask:0xf
	s_nop 1
	v_add_u32_dpp v45, v45, v45 row_ror:2 row_mask:0xf bank_mask:0xf
	s_nop 1
	v_add_u32_dpp v45, v45, v45 row_ror:4 row_mask:0xf bank_mask:0xf
	s_nop 1
	v_add_u32_dpp v45, v45, v45 row_ror:8 row_mask:0xf bank_mask:0xf
	s_nop 0
	v_cmp_le_u32_e32 vcc, 0x100, v45
	s_nop 1
	v_cndmask_b32_e32 v36, v36, v42, vcc
	v_cndmask_b32_e32 v46, v46, v45, vcc
	v_cndmask_b32_e32 v47, v47, v44, vcc
	v_or_b32_e32 v42, 0x4040404, v36
	v_subrev_u32_e32 v43, 0x80808080, v42
	v_mov_b32_e32 v44, 0
	v_sub_u32_e32 v41, v48, v43
	v_and_b32_e32 v41, 0x80808080, v41
	v_bcnt_u32_b32 v44, v41, v44
	v_sub_u32_e32 v45, v49, v43
	v_and_b32_e32 v45, 0x80808080, v45
	v_bcnt_u32_b32 v44, v45, v44
	v_sub_u32_e32 v41, v50, v43
	v_and_b32_e32 v41, 0x80808080, v41
	v_bcnt_u32_b32 v44, v41, v44
	v_sub_u32_e32 v45, v51, v43
	v_and_b32_e32 v45, 0x80808080, v45
	v_bcnt_u32_b32 v44, v45, v44
	v_sub_u32_e32 v41, v52, v43
	v_and_b32_e32 v41, 0x80808080, v41
	v_bcnt_u32_b32 v44, v41, v44
	v_sub_u32_e32 v45, v53, v43
	v_and_b32_e32 v45, 0x80808080, v45
	v_bcnt_u32_b32 v44, v45, v44
	v_sub_u32_e32 v41, v54, v43
	v_and_b32_e32 v41, 0x80808080, v41
	v_bcnt_u32_b32 v44, v41, v44
	v_sub_u32_e32 v45, v55, v43
	v_and_b32_e32 v45, 0x80808080, v45
	v_bcnt_u32_b32 v44, v45, v44
	v_mov_b32_e32 v45, v44
	s_nop 1
	v_add_u32_dpp v45, v45, v45 row_ror:1 row_mask:0xf bank_mask:0xf
	s_nop 1
	v_add_u32_dpp v45, v45, v45 row_ror:2 row_mask:0xf bank_mask:0xf
	s_nop 1
	v_add_u32_dpp v45, v45, v45 row_ror:4 row_mask:0xf bank_mask:0xf
	s_nop 1
	v_add_u32_dpp v45, v45, v45 row_ror:8 row_mask:0xf bank_mask:0xf
	s_nop 0
	v_cmp_le_u32_e32 vcc, 0x100, v45
	s_nop 1
	v_cndmask_b32_e32 v36, v36, v42, vcc
	v_cndmask_b32_e32 v46, v46, v45, vcc
	v_cndmask_b32_e32 v47, v47, v44, vcc
	v_or_b32_e32 v42, 0x2020202, v36
	v_subrev_u32_e32 v43, 0x80808080, v42
	v_mov_b32_e32 v44, 0
	v_sub_u32_e32 v41, v48, v43
	v_and_b32_e32 v41, 0x80808080, v41
	v_bcnt_u32_b32 v44, v41, v44
	v_sub_u32_e32 v45, v49, v43
	v_and_b32_e32 v45, 0x80808080, v45
	v_bcnt_u32_b32 v44, v45, v44
	v_sub_u32_e32 v41, v50, v43
	v_and_b32_e32 v41, 0x80808080, v41
	v_bcnt_u32_b32 v44, v41, v44
	v_sub_u32_e32 v45, v51, v43
	v_and_b32_e32 v45, 0x80808080, v45
	v_bcnt_u32_b32 v44, v45, v44
	v_sub_u32_e32 v41, v52, v43
	v_and_b32_e32 v41, 0x80808080, v41
	v_bcnt_u32_b32 v44, v41, v44
	v_sub_u32_e32 v45, v53, v43
	v_and_b32_e32 v45, 0x80808080, v45
	v_bcnt_u32_b32 v44, v45, v44
	v_sub_u32_e32 v41, v54, v43
	v_and_b32_e32 v41, 0x80808080, v41
	v_bcnt_u32_b32 v44, v41, v44
	v_sub_u32_e32 v45, v55, v43
	v_and_b32_e32 v45, 0x80808080, v45
	v_bcnt_u32_b32 v44, v45, v44
	v_mov_b32_e32 v45, v44
	s_nop 1
	v_add_u32_dpp v45, v45, v45 row_ror:1 row_mask:0xf bank_mask:0xf
	s_nop 1
	v_add_u32_dpp v45, v45, v45 row_ror:2 row_mask:0xf bank_mask:0xf
	s_nop 1
	v_add_u32_dpp v45, v45, v45 row_ror:4 row_mask:0xf bank_mask:0xf
	s_nop 1
	v_add_u32_dpp v45, v45, v45 row_ror:8 row_mask:0xf bank_mask:0xf
	s_nop 0
	v_cmp_le_u32_e32 vcc, 0x100, v45
	s_nop 1
	v_cndmask_b32_e32 v36, v36, v42, vcc
	v_cndmask_b32_e32 v46, v46, v45, vcc
	v_cndmask_b32_e32 v47, v47, v44, vcc
	v_or_b32_e32 v42, 0x1010101, v36
	v_subrev_u32_e32 v43, 0x80808080, v42
	v_mov_b32_e32 v44, 0
	v_sub_u32_e32 v41, v48, v43
	v_and_b32_e32 v41, 0x80808080, v41
	v_bcnt_u32_b32 v44, v41, v44
	v_sub_u32_e32 v45, v49, v43
	v_and_b32_e32 v45, 0x80808080, v45
	v_bcnt_u32_b32 v44, v45, v44
	v_sub_u32_e32 v41, v50, v43
	v_and_b32_e32 v41, 0x80808080, v41
	v_bcnt_u32_b32 v44, v41, v44
	v_sub_u32_e32 v45, v51, v43
	v_and_b32_e32 v45, 0x80808080, v45
	v_bcnt_u32_b32 v44, v45, v44
	v_sub_u32_e32 v41, v52, v43
	v_and_b32_e32 v41, 0x80808080, v41
	v_bcnt_u32_b32 v44, v41, v44
	v_sub_u32_e32 v45, v53, v43
	v_and_b32_e32 v45, 0x80808080, v45
	v_bcnt_u32_b32 v44, v45, v44
	v_sub_u32_e32 v41, v54, v43
	v_and_b32_e32 v41, 0x80808080, v41
	v_bcnt_u32_b32 v44, v41, v44
	v_sub_u32_e32 v45, v55, v43
	v_and_b32_e32 v45, 0x80808080, v45
	v_bcnt_u32_b32 v44, v45, v44
	v_mov_b32_e32 v45, v44
	s_nop 1
	v_add_u32_dpp v45, v45, v45 row_ror:1 row_mask:0xf bank_mask:0xf
	s_nop 1
	v_add_u32_dpp v45, v45, v45 row_ror:2 row_mask:0xf bank_mask:0xf
	s_nop 1
	v_add_u32_dpp v45, v45, v45 row_ror:4 row_mask:0xf bank_mask:0xf
	s_nop 1
	v_add_u32_dpp v45, v45, v45 row_ror:8 row_mask:0xf bank_mask:0xf
	s_nop 0
	v_cmp_le_u32_e32 vcc, 0x100, v45
	s_nop 1
	v_cndmask_b32_e32 v36, v36, v42, vcc
	v_cndmask_b32_e32 v46, v46, v45, vcc
	v_cndmask_b32_e32 v47, v47, v44, vcc
	v_and_b32_e32 v41, 0x7f, v36
	v_lshlrev_b32_e32 v41, v39, v41
	v_add_u32_e32 v41, v34, v41
	v_cmp_ge_u32_e32 vcc, 0x118, v46
	v_cmp_eq_u32_e64 s[0:1], 0, v39
	v_lshlrev_b32_e32 v42, v39, v200
	v_add_u32_e32 v42, -1, v42
	s_or_b64 vcc, vcc, s[0:1]
	s_andn2_b64 s[0:1], vcc, s[50:51]
	s_nor_b64 s[2:3], vcc, s[50:51]
	s_or_b64 s[50:51], s[50:51], vcc
	v_add_u32_e64 v42, v41, v42 clamp
	v_min_u32_e32 v42, v42, v35
	v_cndmask_b32_e64 v37, v37, v41, s[0:1]
	v_cndmask_b32_e64 v62, v62, v47, s[0:1]
	v_cndmask_b32_e64 v35, v35, v42, s[2:3]
	v_cndmask_b32_e64 v34, v34, v41, s[2:3]
	s_cmp_eq_u64 s[50:51], -1
	s_cbranch_scc0 .Lp2apr1_iter
	s_mov_b64 exec, s[22:23]
	v_mov_b32_e32 v61, v62
	s_nop 1
	v_add_u32_dpp v61, v61, v61 row_shr:1 row_mask:0xf bank_mask:0xf bound_ctrl:1
	s_nop 1
	v_add_u32_dpp v61, v61, v61 row_shr:2 row_mask:0xf bank_mask:0xf bound_ctrl:1
	s_nop 1
	v_add_u32_dpp v61, v61, v61 row_shr:4 row_mask:0xf bank_mask:0xf bound_ctrl:1
	s_nop 1
	v_add_u32_dpp v61, v61, v61 row_shr:8 row_mask:0xf bank_mask:0xf bound_ctrl:1
	v_sub_u32_e32 v62, v61, v62
	v_lshl_add_u32 v41, v62, 2, v59
	v_add_u32_e32 v41, -4, v41
	v_cmpx_ge_u32_e32 vcc, v0, v37
	v_add_u32_e32 v41, 4, v41
	ds_write_b32 v41, v0
	s_mov_b64 exec, s[22:23]
	v_cmpx_ge_u32_e32 vcc, v1, v37
	v_add_u32_e32 v41, 4, v41
	ds_write_b32 v41, v1
	s_mov_b64 exec, s[22:23]
	v_cmpx_ge_u32_e32 vcc, v2, v37
	v_add_u32_e32 v41, 4, v41
	ds_write_b32 v41, v2
	s_mov_b64 exec, s[22:23]
	v_cmpx_ge_u32_e32 vcc, v3, v37
	v_add_u32_e32 v41, 4, v41
	ds_write_b32 v41, v3
	s_mov_b64 exec, s[22:23]
	v_cmpx_ge_u32_e32 vcc, v4, v37
	v_add_u32_e32 v41, 4, v41
	ds_write_b32 v41, v4
	s_mov_b64 exec, s[22:23]
	v_cmpx_ge_u32_e32 vcc, v5, v37
	v_add_u32_e32 v41, 4, v41
	ds_write_b32 v41, v5
	s_mov_b64 exec, s[22:23]
	v_cmpx_ge_u32_e32 vcc, v6, v37
	v_add_u32_e32 v41, 4, v41
	ds_write_b32 v41, v6
	s_mov_b64 exec, s[22:23]
	v_cmpx_ge_u32_e32 vcc, v7, v37
	v_add_u32_e32 v41, 4, v41
	ds_write_b32 v41, v7
	s_mov_b64 exec, s[22:23]
	v_cmpx_ge_u32_e32 vcc, v8, v37
	v_add_u32_e32 v41, 4, v41
	ds_write_b32 v41, v8
	s_mov_b64 exec, s[22:23]
	v_cmpx_ge_u32_e32 vcc, v9, v37
	v_add_u32_e32 v41, 4, v41
	ds_write_b32 v41, v9
	s_mov_b64 exec, s[22:23]
	v_cmpx_ge_u32_e32 vcc, v10, v37
	v_add_u32_e32 v41, 4, v41
	ds_write_b32 v41, v10
	s_mov_b64 exec, s[22:23]
	v_cmpx_ge_u32_e32 vcc, v11, v37
	v_add_u32_e32 v41, 4, v41
	ds_write_b32 v41, v11
	s_mov_b64 exec, s[22:23]
	v_cmpx_ge_u32_e32 vcc, v12, v37
	v_add_u32_e32 v41, 4, v41
	ds_write_b32 v41, v12
	s_mov_b64 exec, s[22:23]
	v_cmpx_ge_u32_e32 vcc, v13, v37
	v_add_u32_e32 v41, 4, v41
	ds_write_b32 v41, v13
	s_mov_b64 exec, s[22:23]
	v_cmpx_ge_u32_e32 vcc, v14, v37
	v_add_u32_e32 v41, 4, v41
	ds_write_b32 v41, v14
	s_mov_b64 exec, s[22:23]
	v_cmpx_ge_u32_e32 vcc, v15, v37
	v_add_u32_e32 v41, 4, v41
	ds_write_b32 v41, v15
	s_mov_b64 exec, s[22:23]
	v_cmpx_ge_u32_e32 vcc, v16, v37
	v_add_u32_e32 v41, 4, v41
	ds_write_b32 v41, v16
	s_mov_b64 exec, s[22:23]
	v_cmpx_ge_u32_e32 vcc, v17, v37
	v_add_u32_e32 v41, 4, v41
	ds_write_b32 v41, v17
	s_mov_b64 exec, s[22:23]
	v_cmpx_ge_u32_e32 vcc, v18, v37
	v_add_u32_e32 v41, 4, v41
	ds_write_b32 v41, v18
	s_mov_b64 exec, s[22:23]
	v_cmpx_ge_u32_e32 vcc, v19, v37
	v_add_u32_e32 v41, 4, v41
	ds_write_b32 v41, v19
	s_mov_b64 exec, s[22:23]
	v_cmpx_ge_u32_e32 vcc, v20, v37
	v_add_u32_e32 v41, 4, v41
	ds_write_b32 v41, v20
	s_mov_b64 exec, s[22:23]
	v_cmpx_ge_u32_e32 vcc, v21, v37
	v_add_u32_e32 v41, 4, v41
	ds_write_b32 v41, v21
	s_mov_b64 exec, s[22:23]
	v_cmpx_ge_u32_e32 vcc, v22, v37
	v_add_u32_e32 v41, 4, v41
	ds_write_b32 v41, v22
	s_mov_b64 exec, s[22:23]
	v_cmpx_ge_u32_e32 vcc, v23, v37
	v_add_u32_e32 v41, 4, v41
	ds_write_b32 v41, v23
	s_mov_b64 exec, s[22:23]
	v_cmpx_ge_u32_e32 vcc, v24, v37
	v_add_u32_e32 v41, 4, v41
	ds_write_b32 v41, v24
	s_mov_b64 exec, s[22:23]
	v_cmpx_ge_u32_e32 vcc, v25, v37
	v_add_u32_e32 v41, 4, v41
	ds_write_b32 v41, v25
	s_mov_b64 exec, s[22:23]
	v_cmpx_ge_u32_e32 vcc, v26, v37
	v_add_u32_e32 v41, 4, v41
	ds_write_b32 v41, v26
	s_mov_b64 exec, s[22:23]
	v_cmpx_ge_u32_e32 vcc, v27, v37
	v_add_u32_e32 v41, 4, v41
	ds_write_b32 v41, v27
	s_mov_b64 exec, s[22:23]
	v_cmpx_ge_u32_e32 vcc, v28, v37
	v_add_u32_e32 v41, 4, v41
	ds_write_b32 v41, v28
	s_mov_b64 exec, s[22:23]
	v_cmpx_ge_u32_e32 vcc, v29, v37
	v_add_u32_e32 v41, 4, v41
	ds_write_b32 v41, v29
	s_mov_b64 exec, s[22:23]
	v_cmpx_ge_u32_e32 vcc, v30, v37
	v_add_u32_e32 v41, 4, v41
	ds_write_b32 v41, v30
	s_mov_b64 exec, s[22:23]
	v_cmpx_ge_u32_e32 vcc, v31, v37
	v_add_u32_e32 v41, 4, v41
	ds_write_b32 v41, v31
	s_mov_b64 exec, s[22:23]
	s_mov_b64 exec, -1
	v_and_b32_e32 v41, 0xffffe000, v37
	v_ashrrev_i32_e32 v42, 31, v41
	v_not_b32_e32 v42, v42
	v_or_b32_e32 v42, 0x80000000, v42
	v_xor_b32_e32 v63, v41, v42
	s_cmpk_lt_i32 s8, 0x119
	s_cbranch_scc1 .Lp2apr1_o0
	v_readlane_b32 s0, v63, 0
	v_readlane_b32 s74, v37, 0
	v_readlane_b32 s8, v61, 15
	v_mov_b32_e32 v233, s0
.Lp2apr1_o0:
	s_cmpk_lt_i32 s14, 0x119
	s_cbranch_scc1 .Lp2apr1_o1
	v_readlane_b32 s0, v63, 16
	v_readlane_b32 s75, v37, 16
	v_readlane_b32 s14, v61, 31
	v_mov_b32_e32 v234, s0
.Lp2apr1_o1:
	s_cmpk_lt_i32 s13, 0x119
	s_cbranch_scc1 .Lp2apr1_o2
	v_readlane_b32 s0, v63, 32
	v_readlane_b32 s76, v37, 32
	v_readlane_b32 s13, v61, 47
	v_mov_b32_e32 v235, s0
.Lp2apr1_o2:
	s_cmpk_lt_i32 s5, 0x119
	s_cbranch_scc1 .Lp2apr1_o3
	v_readlane_b32 s0, v63, 48
	v_readlane_b32 s77, v37, 48
	v_readlane_b32 s5, v61, 63
	v_mov_b32_e32 v236, s0
